# v17 + P2 queue: static XCD-aware first grab (4 scan units sharing a K stream on one XCD), dynamic thereafter
# baseline (speedup 1.0000x reference)
; #define LAS __attribute__((address_space(3)))
; __device__ __forceinline__ void na_strip(const Params& P, LAS unsigned char* lds, int strip, int hsel, int tid, int lane, int wave) {
;     const bf16_t* PJ = (const bf16_t*)(P.ws + OFF_PROJ);
;     const bf16_t* QA = PJ; const bf16_t* KA = PJ + SEC_STRIDE; const bf16_t* VA = PJ + 2 * SEC_STRIDE; const bf16_t* GA = PJ + 3 * SEC_STRIDE;
;     bf16_t* MIX = (bf16_t*)(P.ws + OFF_MIX);
;     int sq0, h, r0, rows;
;     if (strip < 512) { sq0 = (strip >> 5) * 4096; h = (strip >> 2) & 7; r0 = (strip & 3) * 16; rows = 64; }
;     else { const int v = strip - 512; sq0 = NP; h = v >> 4; r0 = (v & 15) * 16; rows = 256; }
;     const int npairs = hsel < 0 ? 8 : 4; if (hsel > 0) r0 += 8;
;     const int skey = tid >> 3, sc16 = tid & 7;
;     const unsigned kdst = NA_KR + skey * 128 + 16 * (sc16 ^ (skey & 7)), vdst = NA_VR + skey * 128 + 16 * (sc16 ^ (((skey >> 1) & 3) << 1));
;     const size_t ssrc = (size_t)skey * 512 + h * 64 + 8 * sc16;
;     {
;         const int lo = na_start(r0, rows);
;         u32x4 kr[9], vr[9];
; #pragma unroll
;         for (int i = 0; i < 9; ++i) { const int row = min(lo + i, rows - 1); const size_t o = ((size_t)sq0 + (size_t)row * 64) * 512 + ssrc; kr[i] = *(const u32x4*)(KA + o); vr[i] = *(const u32x4*)(VA + o); }
; #pragma unroll
;         for (int i = 0; i < 9; ++i) { const int row = min(lo + i, rows - 1); const unsigned sl = (unsigned)(row % 9) * 8192u;
;             if (lo + i < rows) { *(LAS u32x4*)(lds + sl + kdst) = kr[i]; *(LAS u32x4*)(lds + sl + vdst) = vr[i]; } }
;         LAS float* rpbs = (LAS float*)(lds + NA_RPB);
;         for (int i = tid; i < 465; i += 512) rpbs[i] = P.rpb[h * 465 + i] * LOG2E;
;     }
;     LBAR();
;     const int rsel = wave >> 2, nb = wave & 3;
;     const int g = lane >> 4, l15 = lane & 15, q4 = l15 >> 2, p = lane & 3;
;     const int kstart = nb == 0 ? 0 : (nb == 1 ? 8 : (nb == 2 ? 24 : 32));
;     const int qc = 16 * nb + l15, wsq = min(max(qc - 8, 0), 48);
;     const LAS float* rp = (const LAS float*)(lds + NA_RPB);
;     float msk[2][4]; int bofs[2][4];
; #pragma unroll
;     for (int kt = 0; kt < 2; ++kt)
; #pragma unroll
;         for (int i = 0; i < 4; ++i) { const int kc = kstart + 16 * kt + 4 * g + i; msk[kt][i] = ((kc >= wsq) && (kc < wsq + 16)) ? -NA_SHIFT : -INFINITY; bofs[kt][i] = min(max(kc - qc + 15, 0), 30); }
.LBB0_263:
	s_cmp_lt_i32 s28, 4
	s_cselect_b64 s[40:41], -1, 0
	s_and_b64 s[0:1], s[40:41], s[0:1]
	s_andn2_b64 vcc, exec, s[0:1]
	s_cbranch_vccnz .LBB0_326
	s_add_u32 s42, s22, 0xc000000
	s_addc_u32 s43, s23, 0
	s_add_u32 s44, s22, 0x11000000
	v_lshrrev_b32_e32 v66, 3, v0
	s_addc_u32 s45, s23, 0
	v_xor_b32_e32 v2, v66, v0
	s_add_u32 s46, s22, 0x16000000
	v_and_b32_e32 v4, 7, v0
	v_lshlrev_b32_e32 v1, 7, v66
	v_lshlrev_b32_e32 v2, 4, v2
	s_movk_i32 s0, 0x70
	s_addc_u32 s47, s23, 0
	v_and_or_b32 v67, v2, s0, v1
	v_bitop3_b32 v2, v66, v4, 6 bitop3:0x6c
	s_bfe_u32 s53, s31, 0x20006
	v_and_b32_e32 v85, 15, v0
	v_lshlrev_b32_e32 v2, 4, v2
	s_mov_b32 s0, 0x12000
	s_add_i32 s4, 0, 0x24000
	s_lshr_b32 s52, s31, 8
	v_lshrrev_b32_e32 v5, 4, v180
	v_lshl_or_b32 v103, s53, 4, v85
	v_mov_b32_e32 v71, 0
	v_lshlrev_b32_e32 v3, 3, v4
	v_or3_b32 v81, v1, v2, s0
	s_cmp_eq_u32 s53, 2
	v_sub_u32_e64 v2, v103, 8 clamp
	v_lshlrev_b32_e32 v68, 3, v5
	v_mov_b32_e32 v69, v71
	v_lshl_or_b32 v79, v66, 9, v3
	v_lshl_add_u32 v83, v0, 2, s4
	s_cselect_b32 s54, 24, 32
	v_min_u32_e32 v104, 48, v2
	v_lshlrev_b32_e32 v105, 2, v5
	v_lshl_add_u64 v[2:3], s[22:23], 0, v[68:69]
	s_mov_b64 s[4:5], 0x1b000000
	v_bitop3_b32 v6, v5, v0, 7 bitop3:0x78
	v_bitop3_b32 v4, v5, v4, 4 bitop3:0x36
	s_add_u32 s55, s22, 0x2a000000
	v_lshlrev_b32_e32 v5, 4, v0
	v_lshl_add_u64 v[72:73], v[2:3], 0, s[4:5]
	s_mov_b64 s[4:5], 0x2000000
	s_addc_u32 s64, s23, 0
	s_lshl_b32 s6, s97, 1
	s_and_b32 s7, s97, 0x3fffffe
	v_and_b32_e32 v70, 0xf0, v5
	v_lshlrev_b32_e32 v10, 1, v0
	v_and_b32_e32 v102, 3, v0
	v_lshl_add_u64 v[74:75], v[2:3], 0, s[4:5]
	v_lshl_add_u64 v[2:3], s[22:23], 0, v[70:71]
	s_mov_b64 s[4:5], 0x25000000
	s_add_u32 s65, s22, 0x34000000
	v_and_b32_e32 v10, 32, v10
	v_and_b32_e32 v11, 64, v0
	v_and_b32_e32 v5, 0x70, v5
	v_lshl_add_u64 v[76:77], v[2:3], 0, s[4:5]
	s_addc_u32 s68, s23, 0
	v_bitop3_b32 v5, v10, v5, v11 bitop3:0x36
	s_and_b32 s4, s6, 2
	v_lshlrev_b32_e32 v13, 3, v102
	s_add_i32 s5, 0, 0x14000
	v_add_u32_e32 v111, 0, v5
	v_lshrrev_b32_e32 v11, 3, v180
	v_add_u32_e32 v115, s5, v5
	v_add_u32_e32 v5, s5, v13
	s_lshl_b32 s5, s4, 11
	v_bfe_u32 v87, v0, 2, 2
	v_lshlrev_b32_e32 v107, 4, v4
	v_lshlrev_b32_e32 v4, 3, v0
	v_or_b32_e32 v2, 0x600, v0
	v_and_b32_e32 v11, 2, v11
	v_lshl_or_b32 v116, v85, 7, s5
	s_or_b32 s5, s97, 1
	v_lshrrev_b32_e32 v84, 4, v2
	v_and_b32_e32 v2, 56, v4
	v_bfe_u32 v10, v0, 1, 1
	v_and_or_b32 v12, v0, 12, v11
	v_and_b32_e32 v4, 8, v4
	v_add_u32_e32 v14, 0, v13
	v_lshl_or_b32 v88, s7, 4, v105
	v_lshl_or_b32 v90, s5, 4, v105
	v_or_b32_e32 v13, v68, v87
	s_lshl_b32 s7, s7, 1
	s_lshl_b32 s5, s5, 1
	v_or_b32_e32 v3, 0x200, v0
	v_lshrrev_b32_e32 v7, 2, v0
	v_add_u32_e32 v4, 0, v4
	v_and_or_b32 v11, v66, 1, v11
	v_or_b32_e32 v15, 4, v13
	v_or_b32_e32 v16, 1, v12
	v_bitop3_b32 v17, s7, v12, v10 bitop3:0x36
	v_bitop3_b32 v12, s5, v12, v10 bitop3:0x36
	v_lshrrev_b32_e32 v78, 4, v0
	v_lshrrev_b32_e32 v80, 4, v3
	v_lshrrev_b32_e32 v86, 3, v3
	v_bfe_u32 v3, v0, 6, 2
	v_and_b32_e32 v7, 12, v7
	v_lshl_add_u32 v118, v15, 8, v4
	v_lshlrev_b32_e32 v119, 4, v17
	v_bitop3_b32 v17, s7, v16, v10 bitop3:0x36
	v_lshlrev_b32_e32 v121, 4, v12
	v_bitop3_b32 v10, s5, v16, v10 bitop3:0x36
	v_lshlrev_b32_e32 v12, 7, v15
	v_bitop3_b32 v15, s6, v11, 2 bitop3:0x6c
	v_bitop3_b32 v11, s4, v11, 1 bitop3:0x36
	v_or_b32_e32 v82, 64, v78
	v_bitop3_b32 v3, v7, v85, v3 bitop3:0x36
	v_lshl_add_u32 v117, v13, 8, v4
	v_lshlrev_b32_e32 v120, 4, v17
	v_lshlrev_b32_e32 v122, 4, v10
	v_lshlrev_b32_e32 v10, 7, v13
	v_lshlrev_b32_e32 v125, 5, v15
	v_lshlrev_b32_e32 v126, 5, v11
	v_or_b32_e32 v11, 32, v13
	v_or_b32_e32 v15, 36, v13
	v_or_b32_e32 v16, 64, v13
	v_or_b32_e32 v17, 0x44, v13
	v_or_b32_e32 v18, 0x60, v13
	v_or_b32_e32 v13, 0x64, v13
	s_movk_i32 s0, 0x1d1
	v_lshlrev_b32_e32 v69, 4, v6
	v_lshlrev_b32_e32 v6, 8, v78
	v_lshl_add_u32 v3, v3, 4, 0
	v_lshlrev_b32_e32 v7, 8, v80
	v_lshlrev_b32_e32 v8, 8, v82
	v_lshlrev_b32_e32 v9, 8, v84
	v_lshl_add_u32 v127, v11, 8, v4
	v_lshl_add_u32 v128, v15, 8, v4
	v_lshlrev_b32_e32 v11, 7, v11
	v_lshlrev_b32_e32 v15, 7, v15
	v_lshl_add_u32 v131, v16, 8, v4
	v_lshl_add_u32 v132, v17, 8, v4
	v_lshlrev_b32_e32 v16, 7, v16
	v_lshlrev_b32_e32 v17, 7, v17
	v_lshl_add_u32 v135, v18, 8, v4
	v_lshl_add_u32 v136, v13, 8, v4
	v_lshlrev_b32_e32 v4, 7, v18
	v_lshlrev_b32_e32 v13, 7, v13
	s_add_u32 s69, s22, 0x3e000000
	v_cmp_gt_u32_e64 s[0:1], s0, v0
	s_mov_b32 s49, 0
	v_add_u32_e32 v106, 16, v104
	v_or_b32_e32 v108, 4, v102
	v_or_b32_e32 v109, 8, v102
	v_or_b32_e32 v110, 12, v102
	v_xor_b32_e32 v112, 0x7f, v66
	v_xor_b32_e32 v113, 0x7f, v86
	v_lshlrev_b32_e32 v114, 7, v86
	v_mov_b32_e32 v89, v71
	v_mov_b32_e32 v91, v71
	v_add_u32_e32 v123, v14, v10
	v_add_u32_e32 v124, v14, v12
	v_add_u32_e32 v129, v14, v11
	v_add_u32_e32 v130, v14, v15
	v_add_u32_e32 v133, v14, v16
	v_add_u32_e32 v134, v14, v17
	v_add_u32_e32 v137, v14, v4
	v_add_u32_e32 v138, v14, v13
	v_add_u32_e32 v139, v5, v10
	v_add_u32_e32 v140, v5, v12
	v_add_u32_e32 v141, v5, v11
	v_add_u32_e32 v142, v5, v15
	v_add_u32_e32 v143, v5, v16
	v_add_u32_e32 v144, v5, v17
	v_add_u32_e32 v145, v5, v4
	v_add_u32_e32 v146, v5, v13
	s_addc_u32 s70, s23, 0
	s_add_i32 s71, 0, 0x25800
	s_movk_i32 s72, 0x43f
	s_mov_b64 s[50:51], 0x20000
	s_mov_b32 s24, 0x3f803f80
	s_mov_b32 s73, 0xc2fc0000
	v_lshlrev_b32_e32 v92, 1, v2
	v_mov_b32_e32 v147, 0xff800000
	v_mov_b32_e32 v148, 0xc1600000
	v_mov_b32_e32 v149, 0x42800000
	v_add_u32_e32 v150, v3, v6
	v_add_u32_e32 v151, v3, v7
	v_add_u32_e32 v152, v3, v8
	v_add_u32_e32 v153, v3, v9
	v_not_b32_e32 v154, 63
	s_cmp_lg_u32 s3, 0x100
	s_cbranch_scc1 .LBB0_268
	s_and_b32 s10, s2, 7
	s_lshr_b32 s7, s2, 3
	s_lshr_b32 s6, s7, 2
	s_lshl_b32 s6, s6, 3
	s_add_i32 s6, s6, s10
	s_lshl_b32 s6, s6, 2
	s_and_b32 s7, s7, 3
	s_add_i32 s74, s6, s7
	s_mov_b64 s[4:5], -1
	s_branch .Lp2_decode

; __global__ void __launch_bounds__(512, 2) mk_fwd(Params P, int ph_lo, int ph_hi) {
;     ...
;             __syncthreads();
;             if (tid == 0) misc[0] = atomicAdd(ctr, 1u);
;             __syncthreads();
;             const int unit = (int)misc[0];
;             if (unit >= SCAN_UNITS + 512 + 256) break;
;             if (unit < SCAN_UNITS) scan_unit(P, lds, unit >> 4, (unit >> 2) & 3, (unit >> 1) & 1, unit & 1, tid, lane, wave);
;             else { const int j = unit - SCAN_UNITS - 512; const bool full = j < 0; na_strip(P, lds, full ? unit - SCAN_UNITS : 512 + (j >> 1), full ? -1 : (j & 1), tid, lane, wave); }
.LBB0_272:
	s_or_b64 exec, exec, s[4:5]
	v_mov_b32_e32 v2, s71
	s_waitcnt lgkmcnt(0)
	s_barrier
	ds_read_b32 v2, v2
	s_mov_b64 s[4:5], -1
	s_waitcnt lgkmcnt(0)
	s_cmp_eq_u32 s3, 0x100
	s_cselect_b32 s6, 0x100, 0
	v_add_u32_e32 v2, s6, v2
	v_cmp_lt_i32_e32 vcc, s72, v2
	v_readfirstlane_b32 s74, v2
	s_cbranch_vccnz .LBB0_267
.Lp2_decode:
	s_cmpk_gt_i32 s74, 0x13f
	s_cbranch_scc0 .LBB0_308
	s_add_i32 s4, s74, 0xfffffcc0
	s_lshr_b32 s4, s4, 1
	s_add_i32 s10, s74, 0xfffffec0
	s_add_i32 s11, s4, 0x200
	s_cmpk_gt_u32 s74, 0x33f
	s_cselect_b64 s[4:5], -1, 0
	s_and_b64 s[6:7], s[4:5], exec
	s_cselect_b32 s12, s11, s10
	s_cmpk_gt_u32 s12, 0x1ff
	s_mov_b64 s[6:7], -1
	s_cbranch_scc0 .LBB0_276
	s_add_i32 s6, s12, 0xfffffe00
	s_lshr_b32 s10, s6, 4
	s_lshl_b32 s6, s12, 4
	s_and_b32 s11, s6, 0xf0
	s_mov_b64 s[6:7], 0
